# rwkv scan producer: ushort values written with ds_write_b16 into the high half of zero-initialised f32 LDS slots; 40 of 48 per-chunk shifts removed
# baseline (speedup 1.0000x reference)
; __device__ __forceinline__ void rwkv_load_chunk(RwkvRegs& R, int n, int pw, int b, int col, const bf16_t* RKV, const bf16_t* LO, const bf16_t* Y) {
; #pragma unroll
;     for (int i = 0; i < 8; ++i) { const int tt = pw + 4 * i, m = b * T_ + 32 * n + tt; const bf16_t* zr = RKV + (size_t)m * RKV_LD; const bf16_t* lo = LO + (size_t)m * 2048;
;         R.vr[i] = zr[col]; R.vx[i] = zr[512 + col]; R.vv[i] = zr[1024 + col]; R.ve[i] = lo[col]; R.va[i] = lo[512 + col]; R.vk[i] = Y[(size_t)m * D_ + col]; }
; }
; __device__ __forceinline__ void rwkv_scan(const Ctx& c, const Params& p, int o, int nblk) {
;     ...
;             rwkv_load_chunk(R, 0, pw, b, col, RKV, LO, Y); rwkv_write_chunk(L, R, 0, pw, c.lane);
;             rwkv_load_chunk(R, 1, pw, b, col, RKV, LO, Y);
.LBB0_96:
	s_and_b64 vcc, exec, s[2:3]
	s_cbranch_vccz .LBB0_89
	s_and_b32 s2, s48, 0xffffe000
	v_readlane_b32 s0, v255, 46
	s_add_i32 s59, s0, s2
	s_lshl_b32 s2, s49, 4
	s_lshl_b32 s58, s49, 8
	s_and_b32 s2, s2, 0x1c0
	s_and_b32 s36, s58, 0xffffe000
	v_add_u32_e32 v2, s2, v164
	s_add_i32 s2, s36, s20
	s_ashr_i32 s3, s2, 31
	s_mul_i32 s39, s2, 0xc00
	s_mul_hi_i32 s11, s2, 0xc00
	s_add_u32 s10, s16, s39
	s_addc_u32 s11, s17, s11
	s_lshl_b64 s[18:19], s[2:3], 12
	v_ashrrev_i32_e32 v3, 31, v2
	s_add_u32 s18, s12, s18
	v_lshlrev_b64 v[2:3], 1, v[2:3]
	s_addc_u32 s19, s13, s19
	s_waitcnt vmcnt(0) lgkmcnt(0)
	v_lshl_add_u64 v[48:49], s[18:19], 0, v[2:3]
	s_add_i32 s18, s36, s0
	v_lshl_add_u64 v[4:5], s[74:75], 0, v[2:3]
	v_lshl_add_u64 v[46:47], s[10:11], 0, v[2:3]
	s_lshl_b64 s[10:11], s[2:3], 11
	s_ashr_i32 s19, s18, 31
	s_mul_i32 s3, s18, 0xc00
	v_lshl_add_u64 v[50:51], v[4:5], 0, s[10:11]
	s_mul_hi_i32 s11, s18, 0xc00
	s_add_u32 s10, s16, s3
	s_addc_u32 s11, s17, s11
	s_lshl_b64 s[62:63], s[18:19], 12
	s_add_u32 s62, s12, s62
	s_addc_u32 s63, s13, s63
	v_lshl_add_u64 v[36:37], s[10:11], 0, v[2:3]
	s_lshl_b64 s[10:11], s[18:19], 11
	global_load_ushort v59, v[46:47], off
	v_lshl_add_u64 v[52:53], v[4:5], 0, s[10:11]
	s_add_i32 s10, s2, 8
	s_ashr_i32 s11, s10, 31
	s_add_i32 s36, s39, 0x6000
	v_lshl_add_u64 v[42:43], s[62:63], 0, v[2:3]
	s_mul_hi_i32 s19, s10, 0xc00
	s_add_u32 s62, s16, s36
	s_addc_u32 s63, s17, s19
	s_lshl_b64 s[72:73], s[10:11], 12
	s_add_u32 s72, s12, s72
	s_addc_u32 s73, s13, s73
	s_lshl_b64 s[10:11], s[10:11], 11
	v_lshl_add_u64 v[44:45], v[4:5], 0, s[10:11]
	s_add_i32 s10, s2, 12
	s_ashr_i32 s11, s10, 31
	s_add_i32 s36, s39, 0x9000
	v_lshl_add_u64 v[32:33], s[62:63], 0, v[2:3]
	s_mul_hi_i32 s19, s10, 0xc00
	s_add_u32 s62, s16, s36
	v_lshl_add_u64 v[40:41], s[72:73], 0, v[2:3]
	s_addc_u32 s63, s17, s19
	s_lshl_b64 s[72:73], s[10:11], 12
	s_add_u32 s72, s12, s72
	s_addc_u32 s73, s13, s73
	s_lshl_b64 s[10:11], s[10:11], 11
	v_lshl_add_u64 v[38:39], v[4:5], 0, s[10:11]
	s_add_i32 s10, s2, 16
	s_ashr_i32 s11, s10, 31
	s_add_i32 s36, s39, 0xc000
	v_lshl_add_u64 v[26:27], s[62:63], 0, v[2:3]
	s_mul_hi_i32 s19, s10, 0xc00
	s_add_u32 s62, s16, s36
	v_lshl_add_u64 v[34:35], s[72:73], 0, v[2:3]
	s_addc_u32 s63, s17, s19
	s_lshl_b64 s[72:73], s[10:11], 12
	s_add_u32 s72, s12, s72
	s_addc_u32 s73, s13, s73
	s_lshl_b64 s[10:11], s[10:11], 11
	v_lshl_add_u64 v[30:31], v[4:5], 0, s[10:11]
	s_add_i32 s10, s2, 20
	s_ashr_i32 s11, s10, 31
	s_add_i32 s36, s39, 0xf000
	v_lshl_add_u64 v[20:21], s[62:63], 0, v[2:3]
	s_mul_hi_i32 s19, s10, 0xc00
	s_add_u32 s62, s16, s36
	v_lshl_add_u64 v[28:29], s[72:73], 0, v[2:3]
	s_addc_u32 s63, s17, s19
	s_lshl_b64 s[72:73], s[10:11], 12
	s_add_u32 s72, s12, s72
	s_addc_u32 s73, s13, s73
	s_lshl_b64 s[10:11], s[10:11], 11
	v_lshl_add_u64 v[24:25], v[4:5], 0, s[10:11]
	s_add_i32 s10, s2, 24
	s_ashr_i32 s11, s10, 31
	s_add_i32 s36, s39, 0x12000
	v_lshl_add_u64 v[14:15], s[62:63], 0, v[2:3]
	s_mul_hi_i32 s19, s10, 0xc00
	s_add_u32 s62, s16, s36
	v_lshl_add_u64 v[22:23], s[72:73], 0, v[2:3]
	s_addc_u32 s63, s17, s19
	s_lshl_b64 s[72:73], s[10:11], 12
	s_add_u32 s72, s12, s72
	s_addc_u32 s73, s13, s73
	s_lshl_b64 s[10:11], s[10:11], 11
	v_lshl_add_u64 v[18:19], v[4:5], 0, s[10:11]
	s_add_i32 s10, s2, 28
	s_ashr_i32 s11, s10, 31
	s_add_i32 s39, s39, 0x15000
	v_lshl_add_u64 v[8:9], s[62:63], 0, v[2:3]
	s_mul_hi_i32 s2, s10, 0xc00
	s_add_u32 s62, s16, s39
	v_lshl_add_u64 v[16:17], s[72:73], 0, v[2:3]
	s_addc_u32 s63, s17, s2
	s_lshl_b64 s[72:73], s[10:11], 12
	s_add_u32 s72, s12, s72
	s_addc_u32 s73, s13, s73
	s_lshl_b64 s[10:11], s[10:11], 11
	v_lshl_add_u64 v[6:7], s[62:63], 0, v[2:3]
	v_lshl_add_u64 v[10:11], s[72:73], 0, v[2:3]
	v_lshl_add_u64 v[12:13], v[4:5], 0, s[10:11]
	global_load_ushort v60, v[48:49], off
	global_load_ushort v61, v[46:47], off offset:1024
	s_nop 0
	global_load_ushort v50, v[50:51], off
	s_nop 0
	global_load_ushort v48, v[48:49], off offset:1024
	s_nop 0
	global_load_ushort v46, v[46:47], off offset:2048
	s_nop 0
	global_load_ushort v47, v[36:37], off
	global_load_ushort v49, v[42:43], off
	global_load_ushort v51, v[36:37], off offset:1024
	s_nop 0
	global_load_ushort v52, v[52:53], off
	s_nop 0
	global_load_ushort v42, v[42:43], off offset:1024
	s_nop 0
	global_load_ushort v36, v[36:37], off offset:2048
	s_nop 0
	global_load_ushort v37, v[32:33], off
	global_load_ushort v43, v[40:41], off
	global_load_ushort v53, v[32:33], off offset:1024
	s_nop 0
	global_load_ushort v44, v[44:45], off
	s_nop 0
	global_load_ushort v40, v[40:41], off offset:1024
	s_nop 0
	global_load_ushort v32, v[32:33], off offset:2048
	s_nop 0
	global_load_ushort v33, v[26:27], off
	global_load_ushort v41, v[34:35], off
	global_load_ushort v45, v[26:27], off offset:1024
	s_nop 0
	global_load_ushort v38, v[38:39], off
	s_nop 0
	global_load_ushort v34, v[34:35], off offset:1024
	s_nop 0
	global_load_ushort v26, v[26:27], off offset:2048
	s_nop 0
	global_load_ushort v27, v[20:21], off
	global_load_ushort v35, v[28:29], off
	global_load_ushort v39, v[20:21], off offset:1024
	s_nop 0
	global_load_ushort v30, v[30:31], off
	s_nop 0
	global_load_ushort v28, v[28:29], off offset:1024
	s_nop 0
	global_load_ushort v20, v[20:21], off offset:2048
	s_nop 0
	global_load_ushort v21, v[14:15], off
	global_load_ushort v29, v[22:23], off
	global_load_ushort v31, v[14:15], off offset:1024
	s_nop 0
	global_load_ushort v24, v[24:25], off
	s_nop 0
	global_load_ushort v22, v[22:23], off offset:1024
	s_nop 0
	global_load_ushort v14, v[14:15], off offset:2048
	s_nop 0
	global_load_ushort v15, v[8:9], off
	global_load_ushort v23, v[16:17], off
	global_load_ushort v25, v[8:9], off offset:1024
	s_nop 0
	global_load_ushort v18, v[18:19], off
	s_nop 0
	global_load_ushort v16, v[16:17], off offset:1024
	s_nop 0
	global_load_ushort v8, v[8:9], off offset:2048
	s_nop 0
	global_load_ushort v9, v[6:7], off
	global_load_ushort v17, v[10:11], off
	global_load_ushort v19, v[6:7], off offset:1024
	s_nop 0
	global_load_ushort v12, v[12:13], off
	s_nop 0
	global_load_ushort v10, v[10:11], off offset:1024
	s_nop 0
	global_load_ushort v6, v[6:7], off offset:2048
	s_waitcnt vmcnt(0) lgkmcnt(0)
; #define LAS __attribute__((address_space(3)))
; __device__ __forceinline__ float bf2f(bf16_t b) { return asf((unsigned)b << 16); }
; __device__ __forceinline__ void rwkv_write_chunk(LAS float* L, const RwkvRegs& R, int n, int pw, int lane) {
;     LAS float* st = L + (n & 1) * 12288;
; #pragma unroll
;     for (int i = 0; i < 8; ++i) { const int tt = pw + 4 * i; LAS float* q = st + tt * 64 + lane;
;         q[0] = bf2f(R.vr[i]); q[2048] = __expf(-bf2f(R.ve[i])); q[4096] = bf2f(R.vx[i]); q[6144] = bf2f(R.vk[i]); q[8192] = bf2f(R.va[i]); q[10240] = bf2f(R.vv[i]); }
; }
; __device__ __forceinline__ void rwkv_scan(const Ctx& c, const Params& p, int o, int nblk) {
;     ...
;             rwkv_load_chunk(R, 0, pw, b, col, RKV, LO, Y); rwkv_write_chunk(L, R, 0, pw, c.lane);
;             rwkv_load_chunk(R, 1, pw, b, col, RKV, LO, Y);
	v_lshlrev_b32_e32 v59, 16, v59
	s_add_i32 s10, s18, 28
	s_ashr_i32 s11, s10, 31
	s_add_i32 s19, s3, 0x15000
	s_mul_hi_i32 s2, s10, 0xc00
	s_add_u32 s62, s16, s19
	s_addc_u32 s63, s17, s2
	s_lshl_b64 s[72:73], s[10:11], 12
	s_add_u32 s72, s12, s72
	s_addc_u32 s73, s13, s73
	s_lshl_b64 s[10:11], s[10:11], 11
	s_add_i32 s19, s3, 0x18000
	s_movk_i32 s46, 0xf800
	v_lshlrev_b32_e32 v7, 16, v60
	v_mul_f32_e32 v7, 0xbfb8aa3b, v7
	v_exp_f32_e32 v7, v7
	v_lshlrev_b32_e32 v11, 16, v61
	v_lshlrev_b32_e32 v13, 16, v50
	v_lshlrev_b32_e32 v47, 16, v47
	ds_write2st64_b32 v56, v59, v47 offset1:4
	v_lshlrev_b32_e32 v47, 16, v49
	v_mul_f32_e32 v47, 0xbfb8aa3b, v47
	v_exp_f32_e32 v47, v47
	v_lshlrev_b32_e32 v48, 16, v48
	v_lshlrev_b32_e32 v46, 16, v46
	ds_write2st64_b32 v56, v7, v47 offset0:32 offset1:36
	v_lshlrev_b32_e32 v7, 16, v51
	ds_write2st64_b32 v56, v11, v7 offset0:64 offset1:68
	v_lshlrev_b32_e32 v7, 16, v52
	ds_write2st64_b32 v56, v13, v7 offset0:96 offset1:100
	v_lshlrev_b32_e32 v7, 16, v42
	ds_write2st64_b32 v56, v48, v7 offset0:128 offset1:132
	v_lshlrev_b32_e32 v7, 16, v36
	ds_write2st64_b32 v56, v46, v7 offset0:160 offset1:164
	v_lshlrev_b32_e32 v7, 16, v37
	v_lshlrev_b32_e32 v33, 16, v33
	v_lshlrev_b32_e32 v11, 16, v43
	ds_write2st64_b32 v56, v7, v33 offset0:8 offset1:12
	v_lshlrev_b32_e32 v7, 16, v41
	v_mul_f32_e32 v11, 0xbfb8aa3b, v11
	v_mul_f32_e32 v7, 0xbfb8aa3b, v7
	v_exp_f32_e32 v11, v11
	v_exp_f32_e32 v7, v7
	v_lshlrev_b32_e32 v13, 16, v53
	v_lshlrev_b32_e32 v36, 16, v44
	v_lshlrev_b32_e32 v37, 16, v40
	ds_write2st64_b32 v56, v11, v7 offset0:40 offset1:44
	v_lshlrev_b32_e32 v7, 16, v45
	ds_write2st64_b32 v56, v13, v7 offset0:72 offset1:76
	v_lshlrev_b32_e32 v7, 16, v38
	ds_write2st64_b32 v56, v36, v7 offset0:104 offset1:108
	v_lshlrev_b32_e32 v7, 16, v34
	v_lshlrev_b32_e32 v32, 16, v32
	ds_write2st64_b32 v56, v37, v7 offset0:136 offset1:140
	v_lshlrev_b32_e32 v7, 16, v26
	ds_write2st64_b32 v56, v32, v7 offset0:168 offset1:172
	v_lshlrev_b32_e32 v7, 16, v27
	v_lshlrev_b32_e32 v21, 16, v21
	v_lshlrev_b32_e32 v11, 16, v35
	ds_write2st64_b32 v56, v7, v21 offset0:16 offset1:20
	v_lshlrev_b32_e32 v7, 16, v29
	v_mul_f32_e32 v11, 0xbfb8aa3b, v11
	v_mul_f32_e32 v7, 0xbfb8aa3b, v7
	v_exp_f32_e32 v11, v11
	v_exp_f32_e32 v7, v7
	v_lshlrev_b32_e32 v13, 16, v39
	v_lshlrev_b32_e32 v26, 16, v30
	v_lshlrev_b32_e32 v27, 16, v28
	ds_write2st64_b32 v56, v11, v7 offset0:48 offset1:52
	v_lshlrev_b32_e32 v7, 16, v31
	ds_write2st64_b32 v56, v13, v7 offset0:80 offset1:84
	v_lshlrev_b32_e32 v7, 16, v24
	ds_write2st64_b32 v56, v26, v7 offset0:112 offset1:116
	v_lshlrev_b32_e32 v7, 16, v22
	v_lshlrev_b32_e32 v20, 16, v20
	ds_write2st64_b32 v56, v27, v7 offset0:144 offset1:148
	v_lshlrev_b32_e32 v7, 16, v14
	ds_write2st64_b32 v56, v20, v7 offset0:176 offset1:180
	v_lshlrev_b32_e32 v7, 16, v15
	v_lshlrev_b32_e32 v9, 16, v9
	v_lshlrev_b32_e32 v11, 16, v23
	ds_write2st64_b32 v56, v7, v9 offset0:24 offset1:28
	v_lshlrev_b32_e32 v7, 16, v17
	v_mul_f32_e32 v11, 0xbfb8aa3b, v11
	v_mul_f32_e32 v7, 0xbfb8aa3b, v7
	v_exp_f32_e32 v11, v11
	v_exp_f32_e32 v7, v7
	v_lshlrev_b32_e32 v13, 16, v25
	v_lshlrev_b32_e32 v14, 16, v18
	v_lshlrev_b32_e32 v15, 16, v16
	ds_write2st64_b32 v56, v11, v7 offset0:56 offset1:60
	v_lshlrev_b32_e32 v7, 16, v19
	ds_write2st64_b32 v56, v13, v7 offset0:88 offset1:92
	v_lshlrev_b32_e32 v7, 16, v12
	v_lshlrev_b32_e32 v8, 16, v8
	ds_write2st64_b32 v56, v14, v7 offset0:120 offset1:124
	v_lshlrev_b32_e32 v7, 16, v10
	v_lshlrev_b32_e32 v6, 16, v6
	ds_write2st64_b32 v56, v15, v7 offset0:152 offset1:156
	ds_write2st64_b32 v56, v8, v6 offset0:184 offset1:188
	v_lshl_add_u64 v[6:7], s[62:63], 0, v[2:3]
	global_load_ushort v10, v[6:7], off
	global_load_ushort v11, v[6:7], off offset:1024
	global_load_ushort v12, v[6:7], off offset:2048
	v_lshl_add_u64 v[6:7], s[72:73], 0, v[2:3]
	global_load_ushort v13, v[6:7], off
	global_load_ushort v14, v[6:7], off offset:1024
	v_lshl_add_u64 v[6:7], v[4:5], 0, s[10:11]
	s_add_i32 s10, s18, 32
	s_ashr_i32 s11, s10, 31
	s_mul_hi_i32 s2, s10, 0xc00
	s_add_u32 s62, s16, s19
	s_addc_u32 s63, s17, s2
	s_lshl_b64 s[72:73], s[10:11], 12
	s_add_u32 s72, s12, s72
	global_load_ushort v15, v[6:7], off
	s_addc_u32 s73, s13, s73
	v_lshl_add_u64 v[6:7], s[62:63], 0, v[2:3]
	global_load_ushort v16, v[6:7], off
	global_load_ushort v17, v[6:7], off offset:1024
	global_load_ushort v18, v[6:7], off offset:2048
	v_lshl_add_u64 v[6:7], s[72:73], 0, v[2:3]
	s_lshl_b64 s[10:11], s[10:11], 11
	global_load_ushort v19, v[6:7], off
	global_load_ushort v20, v[6:7], off offset:1024
	v_lshl_add_u64 v[6:7], v[4:5], 0, s[10:11]
	s_add_i32 s10, s18, 36
	s_ashr_i32 s11, s10, 31
	s_add_i32 s19, s3, 0x1b000
	s_mul_hi_i32 s2, s10, 0xc00
; __device__ __forceinline__ void rwkv_scan(const Ctx& c, const Params& p, int o, int nblk) {
;     ...
;             rwkv_load_chunk(R, 0, pw, b, col, RKV, LO, Y); rwkv_write_chunk(L, R, 0, pw, c.lane);
;             rwkv_load_chunk(R, 1, pw, b, col, RKV, LO, Y);
	s_add_u32 s62, s16, s19
	s_addc_u32 s63, s17, s2
	s_lshl_b64 s[72:73], s[10:11], 12
	s_add_u32 s72, s12, s72
	global_load_ushort v21, v[6:7], off
	s_addc_u32 s73, s13, s73
	v_lshl_add_u64 v[6:7], s[62:63], 0, v[2:3]
	global_load_ushort v22, v[6:7], off
	global_load_ushort v23, v[6:7], off offset:1024
	global_load_ushort v24, v[6:7], off offset:2048
	v_lshl_add_u64 v[6:7], s[72:73], 0, v[2:3]
	s_lshl_b64 s[10:11], s[10:11], 11
	global_load_ushort v25, v[6:7], off
	global_load_ushort v26, v[6:7], off offset:1024
	v_lshl_add_u64 v[6:7], v[4:5], 0, s[10:11]
	s_add_i32 s10, s18, 40
	s_ashr_i32 s11, s10, 31
	s_add_i32 s19, s3, 0x1e000
	s_mul_hi_i32 s2, s10, 0xc00
	s_add_u32 s62, s16, s19
	s_addc_u32 s63, s17, s2
	s_lshl_b64 s[72:73], s[10:11], 12
	s_add_u32 s72, s12, s72
	global_load_ushort v27, v[6:7], off
	s_addc_u32 s73, s13, s73
	v_lshl_add_u64 v[6:7], s[62:63], 0, v[2:3]
	global_load_ushort v28, v[6:7], off
	global_load_ushort v29, v[6:7], off offset:1024
	global_load_ushort v30, v[6:7], off offset:2048
	v_lshl_add_u64 v[6:7], s[72:73], 0, v[2:3]
	s_lshl_b64 s[10:11], s[10:11], 11
	global_load_ushort v31, v[6:7], off
	global_load_ushort v32, v[6:7], off offset:1024
	v_lshl_add_u64 v[6:7], v[4:5], 0, s[10:11]
	s_add_i32 s10, s18, 44
	s_ashr_i32 s11, s10, 31
	s_add_i32 s19, s3, 0x21000
	s_mul_hi_i32 s2, s10, 0xc00
	s_add_u32 s62, s16, s19
	s_addc_u32 s63, s17, s2
	s_lshl_b64 s[72:73], s[10:11], 12
	s_add_u32 s72, s12, s72
	global_load_ushort v33, v[6:7], off
	s_addc_u32 s73, s13, s73
	v_lshl_add_u64 v[6:7], s[62:63], 0, v[2:3]
	global_load_ushort v34, v[6:7], off
	global_load_ushort v35, v[6:7], off offset:1024
	global_load_ushort v36, v[6:7], off offset:2048
	v_lshl_add_u64 v[6:7], s[72:73], 0, v[2:3]
	s_lshl_b64 s[10:11], s[10:11], 11
	global_load_ushort v37, v[6:7], off
	global_load_ushort v38, v[6:7], off offset:1024
	v_lshl_add_u64 v[6:7], v[4:5], 0, s[10:11]
	s_add_i32 s10, s18, 48
	s_ashr_i32 s11, s10, 31
	s_add_i32 s19, s3, 0x24000
	s_mul_hi_i32 s2, s10, 0xc00
	s_add_u32 s62, s16, s19
	s_addc_u32 s63, s17, s2
	s_lshl_b64 s[72:73], s[10:11], 12
	s_add_u32 s72, s12, s72
	global_load_ushort v39, v[6:7], off
	s_addc_u32 s73, s13, s73
	v_lshl_add_u64 v[6:7], s[62:63], 0, v[2:3]
	global_load_ushort v40, v[6:7], off
	global_load_ushort v41, v[6:7], off offset:1024
	global_load_ushort v42, v[6:7], off offset:2048
	v_lshl_add_u64 v[6:7], s[72:73], 0, v[2:3]
	s_lshl_b64 s[10:11], s[10:11], 11
	global_load_ushort v43, v[6:7], off
	global_load_ushort v44, v[6:7], off offset:1024
	v_lshl_add_u64 v[6:7], v[4:5], 0, s[10:11]
	s_add_i32 s10, s18, 52
	s_ashr_i32 s11, s10, 31
	s_add_i32 s19, s3, 0x27000
	s_mul_hi_i32 s2, s10, 0xc00
	s_add_u32 s62, s16, s19
	s_addc_u32 s63, s17, s2
	s_lshl_b64 s[72:73], s[10:11], 12
	s_add_u32 s72, s12, s72
	global_load_ushort v45, v[6:7], off
	s_addc_u32 s73, s13, s73
	v_lshl_add_u64 v[6:7], s[62:63], 0, v[2:3]
	global_load_ushort v46, v[6:7], off
	global_load_ushort v47, v[6:7], off offset:1024
	global_load_ushort v48, v[6:7], off offset:2048
	v_lshl_add_u64 v[6:7], s[72:73], 0, v[2:3]
	s_lshl_b64 s[10:11], s[10:11], 11
	global_load_ushort v49, v[6:7], off
	global_load_ushort v50, v[6:7], off offset:1024
	v_lshl_add_u64 v[6:7], v[4:5], 0, s[10:11]
	s_add_i32 s10, s18, 56
	s_ashr_i32 s11, s10, 31
	s_add_i32 s3, s3, 0x2a000
	s_mul_hi_i32 s18, s10, 0xc00
	s_add_u32 s2, s16, s3
	s_addc_u32 s3, s17, s18
	s_lshl_b64 s[18:19], s[10:11], 12
	s_add_u32 s18, s12, s18
	global_load_ushort v51, v[6:7], off
	s_addc_u32 s19, s13, s19
	v_lshl_add_u64 v[6:7], s[2:3], 0, v[2:3]
	global_load_ushort v52, v[6:7], off
	global_load_ushort v53, v[6:7], off offset:1024
	global_load_ushort v59, v[6:7], off offset:2048
	v_lshl_add_u64 v[6:7], s[18:19], 0, v[2:3]
	s_lshl_b64 s[2:3], s[10:11], 11
	global_load_ushort v60, v[6:7], off
	global_load_ushort v61, v[6:7], off offset:1024
	v_lshl_add_u64 v[6:7], v[4:5], 0, s[2:3]
	global_load_ushort v62, v[6:7], off
	v_lshl_add_u64 v[6:7], s[16:17], 0, v[2:3]
	v_lshl_add_u64 v[8:9], s[12:13], 0, v[2:3]
	v_mov_b32_e32 v64, 0
	v_mov_b32_e32 v65, 0
	v_mov_b32_e32 v66, 0
	v_mov_b32_e32 v67, 0
	v_and_b32_e32 v68, 0xff, v166
	v_lshlrev_b32_e32 v68, 4, v68
	v_add_u32_e32 v68, s80, v68
	v_add_u32_e32 v68, 0xc000, v68
	ds_write_b128 v68, v[64:67] offset:0
	ds_write_b128 v68, v[64:67] offset:4096
	ds_write_b128 v68, v[64:67] offset:16384
	ds_write_b128 v68, v[64:67] offset:20480
	ds_write_b128 v68, v[64:67] offset:24576
	ds_write_b128 v68, v[64:67] offset:28672
	ds_write_b128 v68, v[64:67] offset:32768
	ds_write_b128 v68, v[64:67] offset:36864
	ds_write_b128 v68, v[64:67] offset:40960
	ds_write_b128 v68, v[64:67] offset:45056
	s_mov_b32 s72, 0
	s_mov_b32 s2, 0
	s_branch .LBB0_99

; #define LAS __attribute__((address_space(3)))
; __device__ __forceinline__ float bf2f(bf16_t b) { return asf((unsigned)b << 16); }
; __device__ __forceinline__ void rwkv_write_chunk(LAS float* L, const RwkvRegs& R, int n, int pw, int lane) {
;     LAS float* st = L + (n & 1) * 12288;
; #pragma unroll
;     for (int i = 0; i < 8; ++i) { const int tt = pw + 4 * i; LAS float* q = st + tt * 64 + lane;
;         q[0] = bf2f(R.vr[i]); q[2048] = __expf(-bf2f(R.ve[i])); q[4096] = bf2f(R.vx[i]); q[6144] = bf2f(R.vk[i]); q[8192] = bf2f(R.va[i]); q[10240] = bf2f(R.vv[i]); }
; }
.LBB0_99:
	s_waitcnt lgkmcnt(0)
	s_barrier
	s_add_i32 s10, s2, 1
	s_cmpk_eq_i32 s72, 0x1fe0
	s_cbranch_scc1 .LBB0_101
	s_bitcmp1_b32 s10, 0
	s_cselect_b32 s3, 0xc000, 0
	v_add_u32_e32 v63, s3, v56
	s_waitcnt vmcnt(0) lgkmcnt(0)
	v_lshlrev_b32_e32 v64, 16, v13
	v_lshlrev_b32_e32 v65, 16, v19
	v_mul_f32_e32 v64, 0xbfb8aa3b, v64
	v_mul_f32_e32 v65, 0xbfb8aa3b, v65
	v_exp_f32_e32 v64, v64
	v_exp_f32_e32 v65, v65
	ds_write_b16 v63, v10 offset:2
	ds_write_b16 v63, v16 offset:1026
	ds_write_b16 v63, v11 offset:16386
	ds_write_b16 v63, v17 offset:17410
	ds_write2st64_b32 v63, v64, v65 offset0:32 offset1:36
	ds_write_b16 v63, v15 offset:24578
	ds_write_b16 v63, v21 offset:25602
	ds_write_b16 v63, v14 offset:32770
	ds_write_b16 v63, v20 offset:33794
	ds_write_b16 v63, v12 offset:40962
	ds_write_b16 v63, v18 offset:41986
	v_lshlrev_b32_e32 v64, 16, v25
	v_lshlrev_b32_e32 v65, 16, v31
	v_mul_f32_e32 v64, 0xbfb8aa3b, v64
	v_mul_f32_e32 v65, 0xbfb8aa3b, v65
	v_exp_f32_e32 v64, v64
	v_exp_f32_e32 v65, v65
	ds_write_b16 v63, v22 offset:2050
	ds_write_b16 v63, v28 offset:3074
	ds_write_b16 v63, v23 offset:18434
	ds_write_b16 v63, v29 offset:19458
	ds_write2st64_b32 v63, v64, v65 offset0:40 offset1:44
	ds_write_b16 v63, v27 offset:26626
	ds_write_b16 v63, v33 offset:27650
	ds_write_b16 v63, v26 offset:34818
	ds_write_b16 v63, v32 offset:35842
	ds_write_b16 v63, v24 offset:43010
	ds_write_b16 v63, v30 offset:44034
	v_lshlrev_b32_e32 v64, 16, v37
	v_lshlrev_b32_e32 v65, 16, v43
	v_mul_f32_e32 v64, 0xbfb8aa3b, v64
	v_mul_f32_e32 v65, 0xbfb8aa3b, v65
	v_exp_f32_e32 v64, v64
	v_exp_f32_e32 v65, v65
	ds_write_b16 v63, v34 offset:4098
	ds_write_b16 v63, v40 offset:5122
	ds_write_b16 v63, v35 offset:20482
	ds_write_b16 v63, v41 offset:21506
	ds_write2st64_b32 v63, v64, v65 offset0:48 offset1:52
	ds_write_b16 v63, v39 offset:28674
	ds_write_b16 v63, v45 offset:29698
	ds_write_b16 v63, v38 offset:36866
	ds_write_b16 v63, v44 offset:37890
	ds_write_b16 v63, v36 offset:45058
	ds_write_b16 v63, v42 offset:46082
	v_lshlrev_b32_e32 v64, 16, v49
	v_lshlrev_b32_e32 v65, 16, v60
	v_mul_f32_e32 v64, 0xbfb8aa3b, v64
	v_mul_f32_e32 v65, 0xbfb8aa3b, v65
	v_exp_f32_e32 v64, v64
	v_exp_f32_e32 v65, v65
	ds_write_b16 v63, v46 offset:6146
	ds_write_b16 v63, v52 offset:7170
	ds_write_b16 v63, v47 offset:22530
	ds_write_b16 v63, v53 offset:23554
	ds_write2st64_b32 v63, v64, v65 offset0:56 offset1:60
	ds_write_b16 v63, v51 offset:30722
	ds_write_b16 v63, v62 offset:31746
	ds_write_b16 v63, v50 offset:38914
	ds_write_b16 v63, v61 offset:39938
	ds_write_b16 v63, v48 offset:47106
	ds_write_b16 v63, v59 offset:48130
